# MLA loop: next-tile K/V LDS-DMA issued earlier (all inside the QK phase) so they land before the tile-end wait
# speedup vs baseline: 1.0024x; 1.0004x over previous
.LBB0_1425:
	s_add_i32 s13, s74, 0x8000
	s_mov_b32 s14, m0
	s_mov_b32 m0, s13
	s_nop 0
	global_load_lds_dwordx4 v[168:169], off
	s_mov_b32 m0, s14
	ds_read_b128 v[218:221], v193
	ds_read_b128 v[222:225], v193 offset:1024
	ds_read_b128 v[226:229], v193 offset:2048
	ds_read_b128 v[230:233], v193 offset:3072
	s_waitcnt lgkmcnt(9)
	v_mfma_f32_32x32x16_bf16 v[114:129], v[178:181], v[158:161], v[82:97]
	s_waitcnt lgkmcnt(8)
	v_mfma_f32_32x32x16_bf16 v[98:113], v[214:217], v[158:161], v[82:97]
	ds_read_b128 v[178:181], v208
	ds_read_b128 v[214:217], v208 offset:12288
	s_waitcnt lgkmcnt(9)
	v_mfma_f32_32x32x16_bf16 v[114:129], v[238:241], v[154:157], v[114:129]
	s_waitcnt lgkmcnt(8)
	v_mfma_f32_32x32x16_bf16 v[98:113], v[242:245], v[154:157], v[98:113]
	ds_read_b128 v[238:241], v207
	ds_read_b128 v[242:245], v207 offset:12288
	s_waitcnt lgkmcnt(9)
	v_mfma_f32_32x32x16_bf16 v[114:129], v[246:249], v[150:153], v[114:129]
	s_waitcnt lgkmcnt(8)
	v_mfma_f32_32x32x16_bf16 v[98:113], v[250:253], v[150:153], v[98:113]
	ds_read_b128 v[246:249], v206
	ds_read_b128 v[250:253], v206 offset:12288
	s_add_i32 s13, s75, 0x8000
	s_mov_b32 s14, m0
	s_mov_b32 m0, s13
	s_nop 0
	global_load_lds_dwordx4 v[170:171], off
	s_mov_b32 m0, s14
	s_waitcnt lgkmcnt(5)
	v_mfma_f32_32x32x16_bf16 v[114:129], v[178:181], v[146:149], v[114:129]
	s_waitcnt lgkmcnt(4)
	v_mfma_f32_32x32x16_bf16 v[98:113], v[214:217], v[146:149], v[98:113]
	ds_read_b128 v[178:181], v205
	ds_read_b128 v[214:217], v205 offset:12288
	s_waitcnt lgkmcnt(5)
	v_mfma_f32_32x32x16_bf16 v[114:129], v[238:241], v[142:145], v[114:129]
	s_waitcnt lgkmcnt(4)
	v_mfma_f32_32x32x16_bf16 v[98:113], v[242:245], v[142:145], v[98:113]
	ds_read_b128 v[238:241], v204
	ds_read_b128 v[242:245], v204 offset:12288
	s_waitcnt lgkmcnt(5)
	v_mfma_f32_32x32x16_bf16 v[114:129], v[246:249], v[138:141], v[114:129]
	s_waitcnt lgkmcnt(4)
	v_mfma_f32_32x32x16_bf16 v[98:113], v[250:253], v[138:141], v[98:113]
	ds_read_b128 v[246:249], v203
	ds_read_b128 v[250:253], v203 offset:12288
	s_add_i32 s13, s5, 0x8000
	s_mov_b32 s14, m0
	s_mov_b32 m0, s13
	s_nop 0
	global_load_lds_dwordx4 v[172:173], off
	s_mov_b32 m0, s14
	s_waitcnt lgkmcnt(5)
	v_mfma_f32_32x32x16_bf16 v[114:129], v[178:181], v[134:137], v[114:129]
	s_waitcnt lgkmcnt(4)
	v_mfma_f32_32x32x16_bf16 v[98:113], v[214:217], v[134:137], v[98:113]
	ds_read_b128 v[178:181], v202
	ds_read_b128 v[214:217], v202 offset:12288
	s_waitcnt lgkmcnt(5)
	v_mfma_f32_32x32x16_bf16 v[114:129], v[238:241], v[130:133], v[114:129]
	s_waitcnt lgkmcnt(4)
	v_mfma_f32_32x32x16_bf16 v[98:113], v[242:245], v[130:133], v[98:113]
	ds_read_b128 v[238:241], v201
	ds_read_b128 v[242:245], v201 offset:12288
	s_waitcnt lgkmcnt(5)
	v_mfma_f32_32x32x16_bf16 v[114:129], v[246:249], v[218:221], v[114:129]
	s_waitcnt lgkmcnt(4)
	v_mfma_f32_32x32x16_bf16 v[98:113], v[250:253], v[218:221], v[98:113]
	ds_read_b128 v[246:249], v200
	ds_read_b128 v[250:253], v200 offset:12288
	s_add_i32 s13, s86, 0x0
	s_mov_b32 s14, m0
	s_mov_b32 m0, s13
	s_nop 0
	global_load_lds_dwordx4 v[174:175], off
	s_mov_b32 m0, s14
	s_waitcnt lgkmcnt(5)
	v_mfma_f32_32x32x16_bf16 v[114:129], v[178:181], v[222:225], v[114:129]
	s_waitcnt lgkmcnt(4)
	v_mfma_f32_32x32x16_bf16 v[98:113], v[214:217], v[222:225], v[98:113]
	s_waitcnt lgkmcnt(3)
	v_mfma_f32_32x32x16_bf16 v[114:129], v[238:241], v[226:229], v[114:129]
	s_waitcnt lgkmcnt(2)
	v_mfma_f32_32x32x16_bf16 v[98:113], v[242:245], v[226:229], v[98:113]
	s_waitcnt lgkmcnt(1)
	v_mfma_f32_32x32x16_bf16 v[114:129], v[246:249], v[230:233], v[114:129]
	s_waitcnt lgkmcnt(0)
	v_mfma_f32_32x32x16_bf16 v[98:113], v[250:253], v[230:233], v[98:113]
	s_add_i32 s13, s3, 0x0
	s_mov_b32 s14, m0
	s_mov_b32 m0, s13
	s_nop 0
	global_load_lds_dwordx4 v[176:177], off
	s_mov_b32 m0, s14
	s_sub_i32 s0, s12, 64
	s_cmp_le_i32 s0, s96
	s_cbranch_scc1 .LBB0_1427
	v_add_u32_e32 v165, 0x5b, v212
	v_cmp_lt_i32_e32 vcc, -1, v165
	s_nop 4
	v_cndmask_b32_e32 v114, v185, v114, vcc
	v_cmp_lt_i32_e32 vcc, 31, v165
	v_add_u32_e32 v165, 0x5a, v212
	s_nop 0
	v_cndmask_b32_e32 v98, v185, v98, vcc
	v_cmp_lt_i32_e32 vcc, -1, v165
	s_nop 1
	v_cndmask_b32_e32 v115, v185, v115, vcc
	v_cmp_lt_i32_e32 vcc, 31, v165
	v_add_u32_e32 v165, 0x59, v212
	s_nop 0
	v_cndmask_b32_e32 v99, v185, v99, vcc
	v_cmp_lt_i32_e32 vcc, -1, v165
	s_nop 1
	v_cndmask_b32_e32 v116, v185, v116, vcc
	v_cmp_lt_i32_e32 vcc, 31, v165
	v_add_u32_e32 v165, 0x58, v212
	s_nop 0
	v_cndmask_b32_e32 v100, v185, v100, vcc
	v_cmp_lt_i32_e32 vcc, -1, v165
	s_nop 1
	v_cndmask_b32_e32 v117, v185, v117, vcc
	v_cmp_lt_i32_e32 vcc, 31, v165
	v_add_u32_e32 v165, 0x53, v212
	s_nop 0
	v_cndmask_b32_e32 v101, v185, v101, vcc
	v_cmp_lt_i32_e32 vcc, -1, v165
	s_nop 1
	v_cndmask_b32_e32 v118, v185, v118, vcc
	v_cmp_lt_i32_e32 vcc, 31, v165
	v_add_u32_e32 v165, 0x52, v212
	s_nop 0
	v_cndmask_b32_e32 v102, v185, v102, vcc
	v_cmp_lt_i32_e32 vcc, -1, v165
	s_nop 1
	v_cndmask_b32_e32 v119, v185, v119, vcc
	v_cmp_lt_i32_e32 vcc, 31, v165
	v_add_u32_e32 v165, 0x51, v212
	s_nop 0
	v_cndmask_b32_e32 v103, v185, v103, vcc
	v_cmp_lt_i32_e32 vcc, -1, v165
	s_nop 1
	v_cndmask_b32_e32 v120, v185, v120, vcc
	v_cmp_lt_i32_e32 vcc, 31, v165
	v_add_u32_e32 v165, 0x50, v212
	s_nop 0
	v_cndmask_b32_e32 v104, v185, v104, vcc
	v_cmp_lt_i32_e32 vcc, -1, v165
	s_nop 1
	v_cndmask_b32_e32 v121, v185, v121, vcc
	v_cmp_lt_i32_e32 vcc, 31, v165
	v_add_u32_e32 v165, 0x4b, v212
	s_nop 0
	v_cndmask_b32_e32 v105, v185, v105, vcc
	v_cmp_lt_i32_e32 vcc, -1, v165
	s_nop 1
	v_cndmask_b32_e32 v122, v185, v122, vcc
	v_cmp_lt_i32_e32 vcc, 31, v165
	v_add_u32_e32 v165, 0x4a, v212
	s_nop 0
	v_cndmask_b32_e32 v106, v185, v106, vcc
	v_cmp_lt_i32_e32 vcc, -1, v165
	s_nop 1
	v_cndmask_b32_e32 v123, v185, v123, vcc
	v_cmp_lt_i32_e32 vcc, 31, v165
	v_add_u32_e32 v165, 0x49, v212
	s_nop 0
	v_cndmask_b32_e32 v107, v185, v107, vcc
	v_cmp_lt_i32_e32 vcc, -1, v165
	s_nop 1
	v_cndmask_b32_e32 v124, v185, v124, vcc
	v_cmp_lt_i32_e32 vcc, 31, v165
	v_add_u32_e32 v165, 0x48, v212
	s_nop 0
	v_cndmask_b32_e32 v108, v185, v108, vcc
	v_cmp_lt_i32_e32 vcc, -1, v165
	s_nop 1
	v_cndmask_b32_e32 v125, v185, v125, vcc
	v_cmp_lt_i32_e32 vcc, 31, v165
	v_add_u32_e32 v165, 0x43, v212
	s_nop 0
	v_cndmask_b32_e32 v109, v185, v109, vcc
	v_cmp_lt_i32_e32 vcc, -1, v165
	s_nop 1
	v_cndmask_b32_e32 v126, v185, v126, vcc
	v_cmp_lt_i32_e32 vcc, 31, v165
	v_add_u32_e32 v165, 0x42, v212
	s_nop 0
	v_cndmask_b32_e32 v110, v185, v110, vcc
	v_cmp_lt_i32_e32 vcc, -1, v165
	s_nop 1
	v_cndmask_b32_e32 v127, v185, v127, vcc
	v_cmp_lt_i32_e32 vcc, 31, v165
	v_add_u32_e32 v165, 0x41, v212
	s_nop 0
	v_cndmask_b32_e32 v111, v185, v111, vcc
	v_cmp_lt_i32_e32 vcc, -1, v165
	s_nop 1
	v_cndmask_b32_e32 v128, v185, v128, vcc
	v_cmp_lt_i32_e32 vcc, 31, v165
	v_add_u32_e32 v165, 64, v212
	s_nop 0
	v_cndmask_b32_e32 v112, v185, v112, vcc
	v_cmp_lt_i32_e32 vcc, -1, v165
	s_nop 1
	v_cndmask_b32_e32 v129, v185, v129, vcc
	v_cmp_lt_i32_e32 vcc, 31, v165
	s_nop 1
	v_cndmask_b32_e32 v113, v185, v113, vcc

.LBB0_1431:
	v_exp_f32_e32 v114, v114
	v_exp_f32_e32 v215, v98
	v_exp_f32_e32 v98, v115
	v_exp_f32_e32 v115, v99
	v_exp_f32_e32 v99, v116
	v_exp_f32_e32 v116, v100
	v_exp_f32_e32 v100, v117
	v_exp_f32_e32 v117, v101
	v_exp_f32_e32 v101, v118
	v_exp_f32_e32 v118, v102
	v_exp_f32_e32 v102, v119
	v_exp_f32_e32 v119, v103
	v_exp_f32_e32 v103, v120
	v_exp_f32_e32 v120, v104
	v_exp_f32_e32 v104, v121
	v_exp_f32_e32 v121, v105
	v_exp_f32_e32 v105, v122
	v_exp_f32_e32 v122, v106
	v_exp_f32_e32 v106, v123
	v_exp_f32_e32 v123, v107
	v_exp_f32_e32 v107, v124
	v_exp_f32_e32 v124, v108
	v_exp_f32_e32 v108, v125
	v_exp_f32_e32 v125, v109
	v_exp_f32_e32 v109, v126
	v_exp_f32_e32 v126, v110
	v_exp_f32_e32 v110, v127
	v_exp_f32_e32 v127, v111
	v_exp_f32_e32 v111, v128
	v_exp_f32_e32 v128, v112
	v_exp_f32_e32 v112, v129
	v_add_f32_e32 v129, v114, v215
	v_add_f32_e32 v213, v98, v115
	v_add_f32_e32 v214, v99, v116
	v_add_f32_e32 v216, v100, v117
	v_exp_f32_e32 v113, v113
	v_add_f32_e32 v129, v129, v101
	v_add_f32_e32 v213, v213, v102
	v_add_f32_e32 v214, v214, v103
	v_add_f32_e32 v216, v216, v104
	v_mov_b32_e32 v165, v163
	v_add_f32_e32 v129, v129, v118
	v_add_f32_e32 v213, v213, v119
	v_add_f32_e32 v214, v214, v120
	v_add_f32_e32 v216, v216, v121
	v_mov_b32_e32 v167, v163
	v_add_f32_e32 v129, v129, v105
	v_add_f32_e32 v213, v213, v106
	v_add_f32_e32 v214, v214, v107
	v_add_f32_e32 v216, v216, v108
	v_lshl_add_u64 v[168:169], v[168:169], 0, v[162:163]
	v_add_f32_e32 v129, v129, v122
	v_add_f32_e32 v213, v213, v123
	v_add_f32_e32 v214, v214, v124
	v_add_f32_e32 v216, v216, v125
	v_lshl_add_u64 v[170:171], v[170:171], 0, v[164:165]
	v_add_f32_e32 v129, v129, v109
	v_add_f32_e32 v213, v213, v110
	v_add_f32_e32 v214, v214, v111
	v_add_f32_e32 v216, v216, v112
	v_lshl_add_u64 v[172:173], v[172:173], 0, v[166:167]
	v_add_f32_e32 v129, v129, v126
	v_add_f32_e32 v213, v213, v127
	v_add_f32_e32 v214, v214, v128
	v_add_f32_e32 v216, v216, v113
	v_lshl_add_u64 v[180:181], v[174:175], 0, s[76:77]
	v_add_f32_e32 v129, v129, v213
	v_add_f32_e32 v213, v214, v216
	v_lshl_add_u64 v[178:179], v[176:177], 0, s[76:77]
	v_add_f32_e32 v213, v129, v213
	v_cvt_pk_bf16_f32 v98, v114, v98
	v_cvt_pk_bf16_f32 v99, v99, v100
	v_cvt_pk_bf16_f32 v100, v101, v102
	v_cvt_pk_bf16_f32 v101, v103, v104
	v_cvt_pk_bf16_f32 v102, v105, v106
	s_nop 0
	v_mov_b32_e32 v214, v213
	s_nop 1
	v_permlane32_swap_b32_e32 v213, v214
	v_cvt_pk_bf16_f32 v103, v107, v108
	v_cvt_pk_bf16_f32 v104, v109, v110
	v_cvt_pk_bf16_f32 v105, v111, v112
	v_cvt_pk_bf16_f32 v106, v215, v115
	v_cvt_pk_bf16_f32 v107, v116, v117
	v_cvt_pk_bf16_f32 v108, v118, v119
	v_cvt_pk_bf16_f32 v109, v120, v121
	v_cvt_pk_bf16_f32 v110, v122, v123
	v_cvt_pk_bf16_f32 v111, v124, v125
	v_cvt_pk_bf16_f32 v112, v126, v127
	v_cvt_pk_bf16_f32 v113, v128, v113
	v_permlane32_swap_b32_e32 v98, v100
	v_permlane32_swap_b32_e32 v99, v101
	v_permlane32_swap_b32_e32 v102, v104
	v_permlane32_swap_b32_e32 v103, v105
	v_permlane32_swap_b32_e32 v106, v108
	v_permlane32_swap_b32_e32 v107, v109
	v_permlane32_swap_b32_e32 v110, v112
	v_permlane32_swap_b32_e32 v111, v113
	ds_read_b64_tr_b16 v[114:115], v190 offset:0x4000
	ds_read_b64_tr_b16 v[116:117], v190 offset:0x4800
	ds_read_b64_tr_b16 v[118:119], v190 offset:0x5000
	ds_read_b64_tr_b16 v[120:121], v190 offset:0x5800
	ds_read_b64_tr_b16 v[122:123], v190 offset:0x6000
	ds_read_b64_tr_b16 v[124:125], v190 offset:0x6800
	ds_read_b64_tr_b16 v[126:127], v190 offset:0x7000
	ds_read_b64_tr_b16 v[128:129], v190 offset:0x7800
	ds_read_b64_tr_b16 v[216:217], v190 offset:0x4200
	ds_read_b64_tr_b16 v[218:219], v190 offset:0x4a00
	ds_read_b64_tr_b16 v[220:221], v190 offset:0x5200
	ds_read_b64_tr_b16 v[222:223], v190 offset:0x5a00
	ds_read_b64_tr_b16 v[224:225], v190 offset:0x6200
	ds_read_b64_tr_b16 v[226:227], v190 offset:0x6a00
	ds_read_b64_tr_b16 v[228:229], v190 offset:0x7200
	ds_read_b64_tr_b16 v[230:231], v190 offset:0x7a00
	s_waitcnt lgkmcnt(8)
	s_nop 0
	v_mfma_f32_32x32x16_bf16 v[18:33], v[98:101], v[114:117], v[18:33]
	v_mfma_f32_32x32x16_bf16 v[18:33], v[102:105], v[118:121], v[18:33]
	v_mfma_f32_32x32x16_bf16 v[18:33], v[106:109], v[122:125], v[18:33]
	v_mfma_f32_32x32x16_bf16 v[18:33], v[110:113], v[126:129], v[18:33]
	ds_read_b64_tr_b16 v[114:115], v190 offset:0x4400
	ds_read_b64_tr_b16 v[116:117], v190 offset:0x4c00
	ds_read_b64_tr_b16 v[118:119], v190 offset:0x5400
	ds_read_b64_tr_b16 v[120:121], v190 offset:0x5c00
	ds_read_b64_tr_b16 v[122:123], v190 offset:0x6400
	ds_read_b64_tr_b16 v[124:125], v190 offset:0x6c00
	ds_read_b64_tr_b16 v[126:127], v190 offset:0x7400
	ds_read_b64_tr_b16 v[128:129], v190 offset:0x7c00
	s_waitcnt lgkmcnt(8)
	v_mfma_f32_32x32x16_bf16 v[34:49], v[98:101], v[216:219], v[34:49]
	v_mfma_f32_32x32x16_bf16 v[34:49], v[102:105], v[220:223], v[34:49]
	v_mfma_f32_32x32x16_bf16 v[34:49], v[106:109], v[224:227], v[34:49]
	v_mfma_f32_32x32x16_bf16 v[34:49], v[110:113], v[228:231], v[34:49]
	ds_read_b64_tr_b16 v[216:217], v190 offset:0x4600
	ds_read_b64_tr_b16 v[218:219], v190 offset:0x4e00
	ds_read_b64_tr_b16 v[220:221], v190 offset:0x5600
	ds_read_b64_tr_b16 v[222:223], v190 offset:0x5e00
	ds_read_b64_tr_b16 v[224:225], v190 offset:0x6600
	ds_read_b64_tr_b16 v[226:227], v190 offset:0x6e00
	ds_read_b64_tr_b16 v[228:229], v190 offset:0x7600
	ds_read_b64_tr_b16 v[230:231], v190 offset:0x7e00
	s_waitcnt lgkmcnt(8)
	v_mfma_f32_32x32x16_bf16 v[50:65], v[98:101], v[114:117], v[50:65]
	v_mfma_f32_32x32x16_bf16 v[50:65], v[102:105], v[118:121], v[50:65]
	v_mfma_f32_32x32x16_bf16 v[50:65], v[106:109], v[122:125], v[50:65]
	v_mfma_f32_32x32x16_bf16 v[50:65], v[110:113], v[126:129], v[50:65]
	s_waitcnt lgkmcnt(0)
	v_mfma_f32_32x32x16_bf16 v[66:81], v[98:101], v[216:219], v[66:81]
	s_waitcnt vmcnt(0)
	s_cmp_lt_u32 s11, s10
	s_cselect_b64 s[0:1], -1, 0
	s_cmp_ge_u32 s11, s10
	s_barrier
	ds_read_b128 v[232:235], v194 offset:32768
	ds_read_b128 v[216:219], v194 offset:45056
	ds_read_b128 v[238:241], v195 offset:32768
	ds_read_b128 v[242:245], v195 offset:45056
	ds_read_b128 v[246:249], v196 offset:32768
	ds_read_b128 v[250:253], v196 offset:45056
	v_mfma_f32_32x32x16_bf16 v[66:81], v[102:105], v[220:223], v[66:81]
	v_mfma_f32_32x32x16_bf16 v[66:81], v[106:109], v[224:227], v[66:81]
	v_mfma_f32_32x32x16_bf16 v[66:81], v[110:113], v[228:231], v[66:81]
	s_cbranch_scc1 .LBB0_1433
	s_add_i32 s13, s86, 0x4000
	s_mov_b32 s14, m0
	s_mov_b32 m0, s13
	s_nop 0
	global_load_lds_dwordx4 v[180:181], off
	s_mov_b32 m0, s14
	s_add_i32 s13, s3, 0x4000
	s_mov_b32 s14, m0
	s_mov_b32 m0, s13
	s_nop 0
	global_load_lds_dwordx4 v[178:179], off
	s_mov_b32 m0, s14
	v_lshl_add_u64 v[174:175], v[174:175], 0, s[30:31]
	v_lshl_add_u64 v[176:177], v[176:177], 0, s[30:31]
	s_branch .LBB0_1434

.Lmla_L2_full:
	ds_read_b128 v[220:223], v193
	ds_read_b128 v[224:227], v193 offset:1024
	ds_read_b128 v[228:231], v193 offset:2048
	ds_read_b128 v[178:181], v193 offset:3072
	s_waitcnt lgkmcnt(9)
	v_mfma_f32_32x32x16_bf16 v[114:129], v[232:235], v[158:161], v[82:97]
	s_waitcnt lgkmcnt(8)
	v_mfma_f32_32x32x16_bf16 v[98:113], v[216:219], v[158:161], v[82:97]
	ds_read_b128 v[232:235], v197 offset:32768
	ds_read_b128 v[216:219], v197 offset:45056
	s_waitcnt lgkmcnt(9)
	v_mfma_f32_32x32x16_bf16 v[114:129], v[238:241], v[154:157], v[114:129]
	s_waitcnt lgkmcnt(8)
	v_mfma_f32_32x32x16_bf16 v[98:113], v[242:245], v[154:157], v[98:113]
	ds_read_b128 v[238:241], v194 offset:32896
	ds_read_b128 v[242:245], v194 offset:45184
	s_waitcnt lgkmcnt(9)
	v_mfma_f32_32x32x16_bf16 v[114:129], v[246:249], v[150:153], v[114:129]
	s_waitcnt lgkmcnt(8)
	v_mfma_f32_32x32x16_bf16 v[98:113], v[250:253], v[150:153], v[98:113]
	ds_read_b128 v[246:249], v195 offset:32896
	ds_read_b128 v[250:253], v195 offset:45184
	s_cmp_ge_u32 s11, s10
	s_cbranch_scc1 .Lspr_k1
	s_add_i32 s13, s74, 0xe000
	s_mov_b32 s14, m0
	s_mov_b32 m0, s13
	s_nop 0
	global_load_lds_dwordx4 v[168:169], off
	s_mov_b32 m0, s14
.Lspr_k1:
	s_waitcnt lgkmcnt(5)
	v_mfma_f32_32x32x16_bf16 v[114:129], v[232:235], v[146:149], v[114:129]
	s_waitcnt lgkmcnt(4)
	v_mfma_f32_32x32x16_bf16 v[98:113], v[216:219], v[146:149], v[98:113]
	ds_read_b128 v[232:235], v196 offset:32896
	ds_read_b128 v[216:219], v196 offset:45184
	s_waitcnt lgkmcnt(5)
	v_mfma_f32_32x32x16_bf16 v[114:129], v[238:241], v[142:145], v[114:129]
	s_waitcnt lgkmcnt(4)
	v_mfma_f32_32x32x16_bf16 v[98:113], v[242:245], v[142:145], v[98:113]
	ds_read_b128 v[238:241], v197 offset:32896
	ds_read_b128 v[242:245], v197 offset:45184
	s_waitcnt lgkmcnt(5)
	v_mfma_f32_32x32x16_bf16 v[114:129], v[246:249], v[138:141], v[114:129]
	s_waitcnt lgkmcnt(4)
	v_mfma_f32_32x32x16_bf16 v[98:113], v[250:253], v[138:141], v[98:113]
	ds_read_b128 v[246:249], v194 offset:33024
	ds_read_b128 v[250:253], v194 offset:45312
	s_cmp_ge_u32 s11, s10
	s_cbranch_scc1 .Lspr_k2
	s_add_i32 s13, s75, 0xe000
	s_mov_b32 s14, m0
	s_mov_b32 m0, s13
	s_nop 0
	global_load_lds_dwordx4 v[170:171], off
	s_mov_b32 m0, s14
.Lspr_k2:
	s_waitcnt lgkmcnt(5)
	v_mfma_f32_32x32x16_bf16 v[114:129], v[232:235], v[134:137], v[114:129]
	s_waitcnt lgkmcnt(4)
	v_mfma_f32_32x32x16_bf16 v[98:113], v[216:219], v[134:137], v[98:113]
	ds_read_b128 v[232:235], v195 offset:33024
	ds_read_b128 v[216:219], v195 offset:45312
	s_waitcnt lgkmcnt(5)
	v_mfma_f32_32x32x16_bf16 v[114:129], v[238:241], v[130:133], v[114:129]
	s_waitcnt lgkmcnt(4)
	v_mfma_f32_32x32x16_bf16 v[98:113], v[242:245], v[130:133], v[98:113]
	ds_read_b128 v[238:241], v196 offset:33024
	ds_read_b128 v[242:245], v196 offset:45312
	s_waitcnt lgkmcnt(5)
	v_mfma_f32_32x32x16_bf16 v[114:129], v[246:249], v[220:223], v[114:129]
	s_waitcnt lgkmcnt(4)
	v_mfma_f32_32x32x16_bf16 v[98:113], v[250:253], v[220:223], v[98:113]
	ds_read_b128 v[246:249], v197 offset:33024
	ds_read_b128 v[250:253], v197 offset:45312
	s_waitcnt lgkmcnt(5)
	v_mfma_f32_32x32x16_bf16 v[114:129], v[232:235], v[224:227], v[114:129]
	s_waitcnt lgkmcnt(4)
	v_mfma_f32_32x32x16_bf16 v[98:113], v[216:219], v[224:227], v[98:113]
	s_waitcnt lgkmcnt(3)
	v_mfma_f32_32x32x16_bf16 v[114:129], v[238:241], v[228:231], v[114:129]
	s_waitcnt lgkmcnt(2)
	v_mfma_f32_32x32x16_bf16 v[98:113], v[242:245], v[228:231], v[98:113]
	s_waitcnt lgkmcnt(1)
	v_mfma_f32_32x32x16_bf16 v[114:129], v[246:249], v[178:181], v[114:129]
	s_waitcnt lgkmcnt(0)
	v_mfma_f32_32x32x16_bf16 v[98:113], v[250:253], v[178:181], v[98:113]
	s_cmp_ge_u32 s11, s10
	s_cbranch_scc1 .Lspr_k3
	s_add_i32 s13, s5, 0xe000
	s_mov_b32 s14, m0
	s_mov_b32 m0, s13
	s_nop 0
	global_load_lds_dwordx4 v[172:173], off
	s_mov_b32 m0, s14
	v_mov_b32_e32 v165, v163
	v_mov_b32_e32 v167, v163
	v_lshl_add_u64 v[168:169], v[168:169], 0, v[162:163]
	v_lshl_add_u64 v[170:171], v[170:171], 0, v[164:165]
	v_lshl_add_u64 v[172:173], v[172:173], 0, v[166:167]

.LBB0_1440:
	v_exp_f32_e32 v114, v114
	v_exp_f32_e32 v167, v98
	v_exp_f32_e32 v98, v115
	v_exp_f32_e32 v115, v99
	v_exp_f32_e32 v99, v116
	v_exp_f32_e32 v116, v100
	v_exp_f32_e32 v100, v117
	v_exp_f32_e32 v117, v101
	v_exp_f32_e32 v101, v118
	v_exp_f32_e32 v118, v102
	v_exp_f32_e32 v102, v119
	v_exp_f32_e32 v119, v103
	v_exp_f32_e32 v103, v120
	v_exp_f32_e32 v120, v104
	v_exp_f32_e32 v104, v121
	v_exp_f32_e32 v121, v105
	v_exp_f32_e32 v105, v122
	v_exp_f32_e32 v122, v106
	v_exp_f32_e32 v106, v123
	v_exp_f32_e32 v123, v107
	v_exp_f32_e32 v107, v124
	v_exp_f32_e32 v124, v108
	v_exp_f32_e32 v108, v125
	v_exp_f32_e32 v125, v109
	v_exp_f32_e32 v109, v126
	v_exp_f32_e32 v126, v110
	v_exp_f32_e32 v110, v127
	v_exp_f32_e32 v127, v111
	v_exp_f32_e32 v111, v128
	v_exp_f32_e32 v128, v112
	v_exp_f32_e32 v112, v129
	v_add_f32_e32 v129, v114, v167
	v_add_f32_e32 v178, v98, v115
	v_add_f32_e32 v179, v99, v116
	v_add_f32_e32 v180, v100, v117
	v_exp_f32_e32 v113, v113
	v_add_f32_e32 v129, v129, v101
	v_add_f32_e32 v178, v178, v102
	v_add_f32_e32 v179, v179, v103
	v_add_f32_e32 v180, v180, v104
	v_cvt_pk_bf16_f32 v98, v114, v98
	v_cvt_pk_bf16_f32 v99, v99, v100
	s_nop 0
	v_add_f32_e32 v129, v129, v118
	v_add_f32_e32 v178, v178, v119
	v_add_f32_e32 v179, v179, v120
	v_add_f32_e32 v180, v180, v121
	v_cvt_pk_bf16_f32 v100, v101, v102
	v_cvt_pk_bf16_f32 v101, v103, v104
	s_nop 0
	v_add_f32_e32 v129, v129, v105
	v_add_f32_e32 v178, v178, v106
	v_add_f32_e32 v179, v179, v107
	v_add_f32_e32 v180, v180, v108
	v_cvt_pk_bf16_f32 v102, v105, v106
	v_cvt_pk_bf16_f32 v103, v107, v108
	s_nop 0
	v_add_f32_e32 v129, v129, v122
	v_add_f32_e32 v178, v178, v123
	v_add_f32_e32 v179, v179, v124
	v_add_f32_e32 v180, v180, v125
	v_cvt_pk_bf16_f32 v104, v109, v110
	v_cvt_pk_bf16_f32 v105, v111, v112
	s_nop 0
	v_add_f32_e32 v129, v129, v109
	v_add_f32_e32 v178, v178, v110
	v_add_f32_e32 v179, v179, v111
	v_add_f32_e32 v180, v180, v112
	v_cvt_pk_bf16_f32 v106, v167, v115
	v_cvt_pk_bf16_f32 v107, v116, v117
	s_nop 0
	v_add_f32_e32 v129, v129, v126
	v_add_f32_e32 v178, v178, v127
	v_add_f32_e32 v179, v179, v128
	v_add_f32_e32 v180, v180, v113
	v_cvt_pk_bf16_f32 v108, v118, v119
	v_cvt_pk_bf16_f32 v109, v120, v121
	v_cvt_pk_bf16_f32 v110, v122, v123
	s_nop 0
	v_add_f32_e32 v129, v129, v178
	v_cvt_pk_bf16_f32 v111, v124, v125
	v_add_f32_e32 v178, v179, v180
	v_cvt_pk_bf16_f32 v112, v126, v127
	v_cvt_pk_bf16_f32 v113, v128, v113
	v_permlane32_swap_b32_e32 v98, v100
	v_add_f32_e32 v129, v129, v178
	v_permlane32_swap_b32_e32 v99, v101
	v_mov_b32_e32 v178, v129
	s_nop 1
	v_permlane32_swap_b32_e32 v129, v178
	v_add_f32_e32 v129, v129, v178
	v_add_f32_e32 v199, v165, v129
	v_permlane32_swap_b32_e32 v102, v104
	v_permlane32_swap_b32_e32 v103, v105
	v_permlane32_swap_b32_e32 v106, v108
	v_permlane32_swap_b32_e32 v107, v109
	v_permlane32_swap_b32_e32 v110, v112
	v_permlane32_swap_b32_e32 v111, v113
	ds_read_b64_tr_b16 v[114:115], v190 offset:0
	ds_read_b64_tr_b16 v[116:117], v190 offset:0x800
	ds_read_b64_tr_b16 v[118:119], v190 offset:0x1000
	ds_read_b64_tr_b16 v[120:121], v190 offset:0x1800
	ds_read_b64_tr_b16 v[122:123], v190 offset:0x2000
	ds_read_b64_tr_b16 v[124:125], v190 offset:0x2800
	ds_read_b64_tr_b16 v[126:127], v190 offset:0x3000
	ds_read_b64_tr_b16 v[128:129], v190 offset:0x3800
	ds_read_b64_tr_b16 v[178:179], v190 offset:0x200
	ds_read_b64_tr_b16 v[180:181], v190 offset:0xa00
	ds_read_b64_tr_b16 v[214:215], v190 offset:0x1200
	ds_read_b64_tr_b16 v[216:217], v190 offset:0x1a00
	ds_read_b64_tr_b16 v[218:219], v190 offset:0x2200
	ds_read_b64_tr_b16 v[220:221], v190 offset:0x2a00
	ds_read_b64_tr_b16 v[222:223], v190 offset:0x3200
	ds_read_b64_tr_b16 v[224:225], v190 offset:0x3a00
	s_waitcnt lgkmcnt(8)
	s_nop 0
	v_mfma_f32_32x32x16_bf16 v[18:33], v[98:101], v[114:117], v[18:33]
	v_mfma_f32_32x32x16_bf16 v[18:33], v[102:105], v[118:121], v[18:33]
	v_mfma_f32_32x32x16_bf16 v[18:33], v[106:109], v[122:125], v[18:33]
	v_mfma_f32_32x32x16_bf16 v[18:33], v[110:113], v[126:129], v[18:33]
	ds_read_b64_tr_b16 v[114:115], v190 offset:0x400
	ds_read_b64_tr_b16 v[116:117], v190 offset:0xc00
	ds_read_b64_tr_b16 v[118:119], v190 offset:0x1400
	ds_read_b64_tr_b16 v[120:121], v190 offset:0x1c00
	ds_read_b64_tr_b16 v[122:123], v190 offset:0x2400
	ds_read_b64_tr_b16 v[124:125], v190 offset:0x2c00
	ds_read_b64_tr_b16 v[126:127], v190 offset:0x3400
	ds_read_b64_tr_b16 v[128:129], v190 offset:0x3c00
	s_waitcnt lgkmcnt(8)
	v_mfma_f32_32x32x16_bf16 v[34:49], v[98:101], v[178:181], v[34:49]
	v_mfma_f32_32x32x16_bf16 v[34:49], v[102:105], v[214:217], v[34:49]
	v_mfma_f32_32x32x16_bf16 v[34:49], v[106:109], v[218:221], v[34:49]
	v_mfma_f32_32x32x16_bf16 v[34:49], v[110:113], v[222:225], v[34:49]
	ds_read_b64_tr_b16 v[178:179], v190 offset:0x600
	ds_read_b64_tr_b16 v[180:181], v190 offset:0xe00
	ds_read_b64_tr_b16 v[214:215], v190 offset:0x1600
	ds_read_b64_tr_b16 v[216:217], v190 offset:0x1e00
	ds_read_b64_tr_b16 v[218:219], v190 offset:0x2600
	ds_read_b64_tr_b16 v[220:221], v190 offset:0x2e00
	ds_read_b64_tr_b16 v[222:223], v190 offset:0x3600
	ds_read_b64_tr_b16 v[224:225], v190 offset:0x3e00
	s_waitcnt lgkmcnt(8)
	v_mfma_f32_32x32x16_bf16 v[50:65], v[98:101], v[114:117], v[50:65]
	v_mfma_f32_32x32x16_bf16 v[50:65], v[102:105], v[118:121], v[50:65]
	v_mfma_f32_32x32x16_bf16 v[50:65], v[106:109], v[122:125], v[50:65]
	v_mfma_f32_32x32x16_bf16 v[50:65], v[110:113], v[126:129], v[50:65]
	s_waitcnt lgkmcnt(0)
	v_mfma_f32_32x32x16_bf16 v[66:81], v[98:101], v[178:181], v[66:81]
	s_waitcnt vmcnt(0)
	s_addk_i32 s12, 0x80
	s_add_i32 s8, s11, 2
	s_add_i32 s9, s11, 1
	v_add_u32_e32 v212, 0xffffff80, v212
	s_cmp_lt_u32 s9, s10
	v_mfma_f32_32x32x16_bf16 v[66:81], v[102:105], v[214:217], v[66:81]
	s_barrier
	ds_read_b128 v[178:181], v211
	ds_read_b128 v[214:217], v211 offset:12288
	ds_read_b128 v[238:241], v210
	ds_read_b128 v[242:245], v210 offset:12288
	ds_read_b128 v[246:249], v209
	ds_read_b128 v[250:253], v209 offset:12288
	v_mfma_f32_32x32x16_bf16 v[66:81], v[106:109], v[218:221], v[66:81]
	v_mfma_f32_32x32x16_bf16 v[66:81], v[110:113], v[222:225], v[66:81]
	s_cbranch_scc0 .LBB0_1442
	s_mov_b32 s11, s8
	s_branch .LBB0_1425
